# attention epilogue: the four widened dwordx4 stores issued back-to-back at the very end (outputs kept in the dead accumulator quads) instead of one after each column-group pair
# speedup vs baseline: 1.0099x; 1.0099x over previous
; __device__ __forceinline__ unsigned cvt_pk_bf16(float lo, float hi) { const f32x2 v = {lo, hi}; const bf16x2_t b = __builtin_convertvector(v, bf16x2_t); return __builtin_bit_cast(unsigned, b); }
; __device__ __forceinline__ void attn_phase(LAS unsigned char* lds, const bf16_t* Q, const bf16_t* Kb, const bf16_t* Vt, bf16_t* O, const float* relb, const float* qn, const float* kn, int vcu, int G) {
;     ...
;         const float lt = lrun + __shfl_xor(lrun, 32), il = 1.f / lt;
;         bf16_t* op = O + (rowbase + (size_t)qb * 256 + w * 32 + r32) * D + h * 64 + 4 * hi;
; #pragma unroll
;         for (int gq = 0; gq < 4; ++gq) {
;             u32x2 a; a.x = cvt_pk_bf16(o0[4 * gq] * il, o0[4 * gq + 1] * il); a.y = cvt_pk_bf16(o0[4 * gq + 2] * il, o0[4 * gq + 3] * il);
;             u32x2 c; c.x = cvt_pk_bf16(o1[4 * gq] * il, o1[4 * gq + 1] * il); c.y = cvt_pk_bf16(o1[4 * gq + 2] * il, o1[4 * gq + 3] * il);
;             *(u32x2*)(op + 8 * gq) = a; *(u32x2*)(op + 32 + 8 * gq) = c;
;         }
.LBB0_435:
	ds_bpermute_b32 v1, v147, v131
	v_readlane_b32 s12, v252, 57
	v_readlane_b32 s13, v252, 58
	s_lshl_b32 s54, s35, 1
	v_mov_b32_e32 v135, v0
	s_waitcnt lgkmcnt(0)
	v_add_f32_e32 v1, v131, v1
	v_div_scale_f32 v4, s[18:19], v1, v1, 1.0
	v_rcp_f32_e32 v5, v4
	v_div_scale_f32 v6, vcc, 1.0, v1, 1.0
	v_lshl_add_u64 v[2:3], v[136:137], 1, s[12:13]
	v_fma_f32 v7, -v4, v5, 1.0
	v_fmac_f32_e32 v5, v7, v5
	v_mul_f32_e32 v7, v6, v5
	v_fma_f32 v8, -v4, v7, v6
	v_fmac_f32_e32 v7, v8, v5
	v_fma_f32 v4, -v4, v7, v6
	v_div_fmas_f32 v4, v4, v5, v7
	v_div_fixup_f32 v4, v4, v1, 1.0
	v_lshl_add_u64 v[2:3], v[2:3], 0, s[54:55]
	v_lshl_add_u64 v[2:3], v[2:3], 0, v[134:135]
	v_mbcnt_lo_u32_b32 v10, -1, 0
	v_lshrrev_b32_e32 v10, 5, v10
	v_lshlrev_b32_e32 v10, 3, v10
	v_mov_b32_e32 v11, 0
	v_lshl_add_u64 v[2:3], v[2:3], 0, v[10:11]
	v_pk_mul_f32 v[6:7], v[64:65], v[4:5] op_sel_hi:[1,0]
	v_pk_mul_f32 v[8:9], v[66:67], v[4:5] op_sel_hi:[1,0]
	v_cvt_pk_bf16_f32 v64, v6, v7
	v_cvt_pk_bf16_f32 v65, v8, v9
	v_pk_mul_f32 v[8:9], v[68:69], v[4:5] op_sel_hi:[1,0]
	v_pk_mul_f32 v[10:11], v[70:71], v[4:5] op_sel_hi:[1,0]
	v_cvt_pk_bf16_f32 v66, v8, v9
	v_cvt_pk_bf16_f32 v67, v10, v11
	v_pk_mul_f32 v[6:7], v[72:73], v[4:5] op_sel_hi:[1,0]
	v_pk_mul_f32 v[8:9], v[74:75], v[4:5] op_sel_hi:[1,0]
	v_cvt_pk_bf16_f32 v72, v6, v7
	v_cvt_pk_bf16_f32 v73, v8, v9
	v_pk_mul_f32 v[8:9], v[76:77], v[4:5] op_sel_hi:[1,0]
	v_pk_mul_f32 v[10:11], v[78:79], v[4:5] op_sel_hi:[1,0]
	v_cvt_pk_bf16_f32 v74, v8, v9
	v_cvt_pk_bf16_f32 v75, v10, v11
	v_pk_mul_f32 v[6:7], v[48:49], v[4:5] op_sel_hi:[1,0]
	v_pk_mul_f32 v[8:9], v[50:51], v[4:5] op_sel_hi:[1,0]
	v_cvt_pk_bf16_f32 v48, v6, v7
	v_cvt_pk_bf16_f32 v49, v8, v9
	v_pk_mul_f32 v[8:9], v[52:53], v[4:5] op_sel_hi:[1,0]
	v_pk_mul_f32 v[10:11], v[54:55], v[4:5] op_sel_hi:[1,0]
	v_cvt_pk_bf16_f32 v50, v8, v9
	v_cvt_pk_bf16_f32 v51, v10, v11
	v_pk_mul_f32 v[6:7], v[56:57], v[4:5] op_sel_hi:[1,0]
	v_pk_mul_f32 v[8:9], v[58:59], v[4:5] op_sel_hi:[1,0]
	v_cvt_pk_bf16_f32 v56, v6, v7
	v_cvt_pk_bf16_f32 v57, v8, v9
	v_pk_mul_f32 v[8:9], v[60:61], v[4:5] op_sel_hi:[1,0]
	v_pk_mul_f32 v[10:11], v[62:63], v[4:5] op_sel_hi:[1,0]
	v_cvt_pk_bf16_f32 v58, v8, v9
	v_cvt_pk_bf16_f32 v59, v10, v11
	s_add_i32 s34, s34, s56
	s_add_i32 s30, s30, s56
	v_permlane32_swap_b32_e32 v64, v66
	v_permlane32_swap_b32_e32 v65, v67
	v_permlane32_swap_b32_e32 v72, v74
	v_permlane32_swap_b32_e32 v73, v75
	v_permlane32_swap_b32_e32 v48, v50
	v_permlane32_swap_b32_e32 v49, v51
	v_permlane32_swap_b32_e32 v56, v58
	v_permlane32_swap_b32_e32 v57, v59
	s_cmpk_lt_i32 s34, 0x800
	global_store_dwordx4 v[2:3], v[64:67], off
	global_store_dwordx4 v[2:3], v[72:75], off offset:32
	global_store_dwordx4 v[2:3], v[48:51], off offset:64
	global_store_dwordx4 v[2:3], v[56:59], off offset:96
	s_cbranch_scc0 .LBB0_473
